# prep S3 tail: the sixteen serialized 2-byte LDS reads (read, wait, read, wait) of the two K^T store groups issued together with counted waits; on v61
# speedup vs baseline: 1.0053x; 1.0024x over previous
; #define LAS __attribute__((address_space(3)))
; __device__ __forceinline__ unsigned pk2(float lo, float hi) { return pg8::cvt_pk_bf16(lo, hi); }
; __device__ __forceinline__ void prep_task(LAS unsigned char* lds, const PrepP& P, int task, int tid, int lane, int wave) {
;     ...
;     {
;         const int c0 = wave * 16;
;         bf16x8 bv[2], bk[2];
; #pragma unroll
;         for (int ks = 0; ks < 2; ++ks)
; #pragma unroll
;             for (int j = 0; j < 8; ++j) { const int tok = ks * 32 + q8 * 8 + j; bv[ks][j] = (short)Vl[tok * PS + c0 + r]; bk[ks][j] = (short)KBl[tok * PS + c0 + r]; }
; #pragma unroll
;         for (int mt = 0; mt < 4; ++mt) {
;             f32x4 aU = {0.f, 0.f, 0.f, 0.f}, aW = {0.f, 0.f, 0.f, 0.f};
; #pragma unroll
;             for (int ks = 0; ks < 2; ++ks) { if (ks == 1 && mt < 2) continue;
;                 const bf16x8 aT = *(const LAS bf16x8*)(Tl + (mt * 16 + r) * TS + ks * 32 + q8 * 8);
;                 aU = __builtin_amdgcn_mfma_f32_16x16x32_bf16(aT, bv[ks], aU, 0, 0, 0);
;                 aW = __builtin_amdgcn_mfma_f32_16x16x32_bf16(bk[ks], aT, aW, 0, 0, 0); }
;             *(f32x4*)((float*)(trp + TR_U) + ((wave * 4 + mt) * 64 + lane) * 4) = aU;
;             u32x2 o; o.x = pk2(-aW[0], -aW[1]); o.y = pk2(-aW[2], -aW[3]);
;             *(u32x2*)((bf16_t*)(trp + TR_W) + (mt * 16 + r) * 128 + c0 + q8 * 4) = o;
;         }
.LBB0_415:
	v_or_b32_e32 v1, s22, v59
	s_movk_i32 s4, 0x440
	v_mad_u32_u24 v1, v62, s4, v1
	s_waitcnt lgkmcnt(0)
	s_barrier
	v_lshl_add_u32 v1, v1, 1, v58
	ds_read_u16 v4, v1 offset:34816
	ds_read_u16 v16, v1 offset:52224
	ds_read_u16 v5, v1 offset:35088
	ds_read_u16 v17, v1 offset:52496
	ds_read_u16 v6, v1 offset:35360
	ds_read_u16 v18, v1 offset:52768
	ds_read_u16 v7, v1 offset:35632
	ds_read_u16 v19, v1 offset:53040
	ds_read_u16 v2, v1 offset:35904
	s_waitcnt lgkmcnt(10)
	ds_read_u16 v20, v1 offset:53312
	s_waitcnt lgkmcnt(10)
	ds_read_u16 v12, v1 offset:36176
	ds_read_u16 v21, v1 offset:53584
	ds_read_u16 v3, v1 offset:36448
	ds_read_u16 v22, v1 offset:53856
	ds_read_u16 v13, v1 offset:36720
	ds_read_u16 v23, v1 offset:54128
	ds_read_u16 v24, v1 offset:43520
	ds_read_u16 v28, v1 offset:60928
	ds_read_u16 v29, v1 offset:43792
	ds_read_u16 v32, v1 offset:61200
	ds_read_u16 v25, v1 offset:44064
	ds_read_u16 v33, v1 offset:61472
	ds_read_u16 v30, v1 offset:44336
	ds_read_u16 v34, v1 offset:61744
	ds_read_u16 v26, v1 offset:44608
	ds_read_u16 v35, v1 offset:62016
	ds_read_u16 v31, v1 offset:44880
	ds_read_u16 v36, v1 offset:62288
	ds_read_u16 v27, v1 offset:45152
	ds_read_u16 v37, v1 offset:62560
	ds_read_u16 v38, v1 offset:45424
	ds_read_u16 v39, v1 offset:62832
	v_mul_u32_u24_e32 v1, 0x90, v59
	v_add3_u32 v48, v0, v61, v1
	ds_read_b128 v[8:11], v48
	s_waitcnt lgkmcnt(14)
	v_perm_b32 v1, v7, v6, s58
	v_perm_b32 v0, v5, v4, s58
	v_perm_b32 v7, v23, v22, s58
	v_perm_b32 v6, v21, v20, s58
	v_perm_b32 v5, v19, v18, s58
	v_perm_b32 v4, v17, v16, s58
	v_perm_b32 v3, v13, v3, s58
	v_perm_b32 v2, v12, v2, s58
	s_waitcnt lgkmcnt(0)
	v_mfma_f32_16x16x32_bf16 v[16:19], v[4:7], v[8:11], 0
	s_mov_b32 s4, 0x22412000
	v_lshl_or_b32 v152, v59, 8, v60
	v_perm_b32 v26, v31, v26, s58
	v_mfma_f32_16x16x32_bf16 v[12:15], v[8:11], v[0:3], 0
	v_lshl_or_b32 v8, v56, 2, s37
	v_ashrrev_i32_e32 v9, 31, v8
	v_lshl_add_u64 v[8:9], v[8:9], 2, s[26:27]
	v_lshl_add_u64 v[8:9], v[40:41], 0, v[8:9]
	v_add_co_u32_e32 v8, vcc, s4, v8
	v_xor_b32_e32 v10, 0x80000000, v16
	s_nop 0
	v_addc_co_u32_e32 v9, vcc, 0, v9, vcc
	v_xor_b32_e32 v11, 0x80000000, v17
	global_store_dwordx4 v[8:9], v[12:15], off
	s_mov_b32 s4, 0x22401000
	v_perm_b32 v25, v30, v25, s58
	v_cvt_pk_bf16_f32 v12, v10, v11
	v_xor_b32_e32 v10, 0x80000000, v18
	v_xor_b32_e32 v11, 0x80000000, v19
	v_cvt_pk_bf16_f32 v13, v10, v11
	v_lshl_add_u64 v[10:11], s[30:31], 0, v[152:153]
	v_lshl_add_u64 v[10:11], v[40:41], 0, v[10:11]
	v_add_co_u32_e32 v20, vcc, s4, v10
	v_perm_b32 v24, v29, v24, s58
	s_nop 0
	v_addc_co_u32_e32 v21, vcc, 0, v11, vcc
	global_store_dwordx2 v[20:21], v[12:13], off offset:-4096
	ds_read_b128 v[12:15], v48 offset:2304
	s_waitcnt lgkmcnt(0)
	v_mfma_f32_16x16x32_bf16 v[16:19], v[12:15], v[0:3], 0
	v_perm_b32 v31, v39, v37, s58
	v_perm_b32 v30, v36, v35, s58
	v_perm_b32 v29, v34, v33, s58
	v_mfma_f32_16x16x32_bf16 v[12:15], v[4:7], v[12:15], 0
	s_nop 3
	global_store_dwordx4 v[8:9], v[16:19], off offset:1024
	v_perm_b32 v28, v32, v28, s58
	v_perm_b32 v27, v38, v27, s58
	s_mov_b32 s4, 0x22403000
	s_addk_i32 s48, 0x100
	v_xor_b32_e32 v12, 0x80000000, v12
	v_xor_b32_e32 v13, 0x80000000, v13
	v_cvt_pk_bf16_f32 v12, v12, v13
	v_xor_b32_e32 v13, 0x80000000, v14
	v_xor_b32_e32 v14, 0x80000000, v15
	v_cvt_pk_bf16_f32 v13, v13, v14
	global_store_dwordx2 v[20:21], v[12:13], off
	ds_read_b128 v[12:15], v48 offset:4608
	ds_read_b128 v[20:23], v48 offset:4672
	s_waitcnt lgkmcnt(1)
	v_mfma_f32_16x16x32_bf16 v[16:19], v[12:15], v[0:3], 0
	s_addk_i32 s49, 0x800
	s_add_u32 s24, s24, 0x400
	s_addc_u32 s25, s25, 0
	v_mfma_f32_16x16x32_bf16 v[12:15], v[4:7], v[12:15], 0
	s_waitcnt lgkmcnt(0)
; #define LAS __attribute__((address_space(3)))
; __device__ __forceinline__ float bf2f(bf16_t h) { return __uint_as_float((unsigned)h << 16); }
; __device__ __forceinline__ unsigned pk2(float lo, float hi) { return pg8::cvt_pk_bf16(lo, hi); }
; __device__ __forceinline__ u32x4 pack8(const float* v) { u32x4 o; o.x = pk2(v[0], v[1]); o.y = pk2(v[2], v[3]); o.z = pk2(v[4], v[5]); o.w = pk2(v[6], v[7]); return o; }
; __device__ __forceinline__ void prep_task(LAS unsigned char* lds, const PrepP& P, int task, int tid, int lane, int wave) {
;     ...
;         for (int mt = 0; mt < 4; ++mt) {
;             f32x4 aU = {0.f, 0.f, 0.f, 0.f}, aW = {0.f, 0.f, 0.f, 0.f};
; #pragma unroll
;             for (int ks = 0; ks < 2; ++ks) { if (ks == 1 && mt < 2) continue;
;                 const bf16x8 aT = *(const LAS bf16x8*)(Tl + (mt * 16 + r) * TS + ks * 32 + q8 * 8);
;                 aU = __builtin_amdgcn_mfma_f32_16x16x32_bf16(aT, bv[ks], aU, 0, 0, 0);
;                 aW = __builtin_amdgcn_mfma_f32_16x16x32_bf16(bk[ks], aT, aW, 0, 0, 0); }
;             *(f32x4*)((float*)(trp + TR_U) + ((wave * 4 + mt) * 64 + lane) * 4) = aU;
;             u32x2 o; o.x = pk2(-aW[0], -aW[1]); o.y = pk2(-aW[2], -aW[3]);
;             *(u32x2*)((bf16_t*)(trp + TR_W) + (mt * 16 + r) * 128 + c0 + q8 * 4) = o;
;         }
; #pragma unroll
;         for (int ii = 0; ii < 2; ++ii) { const int item = tid + 512 * ii, dk = item & 127, oct = item >> 7; float kv[8];
; #pragma unroll
;             for (int j = 0; j < 8; ++j) kv[j] = bf2f(KTl[(oct * 8 + j) * PS + dk]);
;             *(u32x4*)((bf16_t*)(trp + TR_K) + dk * 64 + oct * 8) = pack8(kv); }
	v_mfma_f32_16x16x32_bf16 v[12:15], v[28:31], v[20:23], v[12:15]
	v_mfma_f32_16x16x32_bf16 v[16:19], v[20:23], v[24:27], v[16:19]
	s_nop 6
	v_xor_b32_e32 v12, 0x80000000, v12
	v_xor_b32_e32 v13, 0x80000000, v13
	v_cvt_pk_bf16_f32 v12, v12, v13
	v_xor_b32_e32 v13, 0x80000000, v14
	v_xor_b32_e32 v14, 0x80000000, v15
	v_cvt_pk_bf16_f32 v13, v13, v14
	v_add_co_u32_e32 v14, vcc, s4, v10
	global_store_dwordx4 v[8:9], v[16:19], off offset:2048
	s_nop 0
	v_addc_co_u32_e32 v15, vcc, 0, v11, vcc
	global_store_dwordx2 v[14:15], v[12:13], off offset:-4096
	ds_read_b128 v[10:13], v48 offset:6912
	s_waitcnt lgkmcnt(0)
	v_mfma_f32_16x16x32_bf16 v[0:3], v[10:13], v[0:3], 0
	v_mfma_f32_16x16x32_bf16 v[4:7], v[4:7], v[10:13], 0
	ds_read_b128 v[10:13], v48 offset:6976
	s_waitcnt lgkmcnt(0)
	v_mfma_f32_16x16x32_bf16 v[0:3], v[10:13], v[24:27], v[0:3]
	s_nop 7
	global_store_dwordx4 v[8:9], v[0:3], off offset:3072
	v_mfma_f32_16x16x32_bf16 v[4:7], v[28:31], v[10:13], v[4:7]
	s_nop 7
	v_xor_b32_e32 v0, 0x80000000, v4
	v_xor_b32_e32 v1, 0x80000000, v5
	v_cvt_pk_bf16_f32 v0, v0, v1
	v_xor_b32_e32 v1, 0x80000000, v6
	v_xor_b32_e32 v2, 0x80000000, v7
	v_cvt_pk_bf16_f32 v1, v1, v2
	v_and_b32_e32 v5, 0x7f, v55
	v_ashrrev_i32_e32 v2, 4, v55
	v_lshl_add_u32 v4, v5, 1, v57
	v_and_b32_e32 v6, -8, v2
	global_store_dwordx2 v[14:15], v[0:1], off
	v_mad_u64_u32 v[0:1], s[4:5], v6, s51, v[4:5]
	v_or_b32_e32 v24, 7, v2
	v_mad_u64_u32 v[24:25], s[4:5], v24, s51, v[4:5]
	v_add_u32_e32 v37, 0x200, v55
	v_ashrrev_i32_e32 v37, 4, v37
	v_and_b32_e32 v38, -8, v37
	v_or_b32_e32 v37, 7, v37
	ds_read_u16 v20, v0
	ds_read_u16 v21, v0 offset:272
	ds_read_u16 v22, v0 offset:544
	ds_read_u16 v23, v0 offset:816
	ds_read_u16 v26, v0 offset:1088
	ds_read_u16 v27, v0 offset:1360
	ds_read_u16 v28, v0 offset:1632
	ds_read_u16 v0, v24
	v_mad_u64_u32 v[38:39], s[4:5], v38, s51, v[4:5]
	v_mad_u64_u32 v[24:25], s[4:5], v37, s51, v[4:5]
	ds_read_u16 v29, v38
	ds_read_u16 v30, v38 offset:272
	ds_read_u16 v31, v38 offset:544
	ds_read_u16 v32, v38 offset:816
	ds_read_u16 v33, v38 offset:1088
	ds_read_u16 v34, v38 offset:1360
	ds_read_u16 v35, v38 offset:1632
	s_waitcnt lgkmcnt(14)
	ds_read_u16 v36, v24
	v_lshlrev_b32_e32 v152, 7, v5
	s_waitcnt lgkmcnt(9)
	v_lshlrev_b32_e32 v3, 16, v20
	v_lshlrev_b32_e32 v7, 16, v21
	v_lshlrev_b32_e32 v8, 16, v22
	v_lshlrev_b32_e32 v9, 16, v23
	v_lshlrev_b32_e32 v10, 16, v26
	v_lshlrev_b32_e32 v11, 16, v27
	v_lshlrev_b32_e32 v12, 16, v28
	v_cvt_pk_bf16_f32 v1, v8, v9
	v_cvt_pk_bf16_f32 v2, v10, v11
	s_waitcnt lgkmcnt(8)
	v_lshlrev_b32_e32 v13, 16, v0
	v_cvt_pk_bf16_f32 v0, v3, v7
	v_ashrrev_i32_e32 v7, 31, v6
	v_lshl_add_u64 v[6:7], v[6:7], 1, v[152:153]
	v_lshl_add_u64 v[6:7], s[26:27], 0, v[6:7]
	v_lshl_add_u64 v[6:7], v[40:41], 0, v[6:7]
	v_add_co_u32_e32 v6, vcc, s59, v6
	v_cvt_pk_bf16_f32 v3, v12, v13
	s_nop 1
	v_addc_co_u32_e32 v7, vcc, 0, v7, vcc
	global_store_dwordx4 v[6:7], v[0:3], off
	s_nop 1
	v_add_u32_e32 v0, 0x200, v55
	v_ashrrev_i32_e32 v2, 4, v0
	v_and_b32_e32 v6, -8, v2
	s_waitcnt lgkmcnt(0)
	v_lshlrev_b32_e32 v3, 16, v29
	v_lshlrev_b32_e32 v5, 16, v30
	v_lshlrev_b32_e32 v7, 16, v31
	v_lshlrev_b32_e32 v8, 16, v32
	v_lshlrev_b32_e32 v9, 16, v33
	v_lshlrev_b32_e32 v10, 16, v34
	v_lshlrev_b32_e32 v11, 16, v35
	v_mov_b32_e32 v0, v36
	v_cvt_pk_bf16_f32 v1, v7, v8
	v_ashrrev_i32_e32 v7, 31, v6
	v_cvt_pk_bf16_f32 v2, v9, v10
	s_waitcnt lgkmcnt(0)
	v_lshlrev_b32_e32 v4, 16, v0
	v_cvt_pk_bf16_f32 v0, v3, v5
	v_cvt_pk_bf16_f32 v3, v11, v4
	v_lshl_add_u64 v[4:5], v[6:7], 1, v[152:153]
	v_lshl_add_u64 v[4:5], s[26:27], 0, v[4:5]
	v_lshl_add_u64 v[4:5], v[40:41], 0, v[4:5]
	s_add_u32 s26, s26, 0x1a00000
	v_add_co_u32_e32 v4, vcc, s59, v4
	s_addc_u32 s27, s27, 0
	s_nop 0
	v_addc_co_u32_e32 v5, vcc, 0, v5, vcc
	s_add_u32 s28, s28, 0x1a00000
	global_store_dwordx4 v[4:5], v[0:3], off
	s_addc_u32 s29, s29, 0
	s_waitcnt lgkmcnt(0)
	s_barrier
	s_add_u32 s30, s30, 0x1a00000
	s_addc_u32 s31, s31, 0
	s_cmpk_gt_i32 s48, 0x2ff
	s_cbranch_scc1 .LBB0_430
